# v109 + E1 steal phase peeks all 8 queue words once and fakes failing tickets for empty queues (no atomic round trips)
# baseline (speedup 1.0000x reference)
; template <class F>
; __device__ __forceinline__ void xcd_queue_run(unsigned* qwords, int nper, char* smem_aux, F fn) {
;     ...
;   for (int dj = 0; dj < 8; dj++) {
;     const int j = (int)((x + dj) & 7u);
;     for (;;) {
;       __syncthreads();
;       if (threadIdx.x == 0) *slot = (int)__hip_atomic_fetch_add(qwords + 64 * j, 1u, __ATOMIC_RELAXED, __HIP_MEMORY_SCOPE_AGENT);
;       __syncthreads();
.Le1_nosig:
	s_mov_b32 s51, s32
	s_mov_b32 s32, -1
	s_mov_b64 s[20:21], exec
	v_mbcnt_lo_u32_b32 v0, s20, 0
	v_mbcnt_hi_u32_b32 v0, s21, v0
	v_cmp_eq_u32_e32 vcc, 0, v0
	s_and_saveexec_b64 s[18:19], vcc
	s_cbranch_execz .LBB0_1272
	s_cmp_eq_u32 s26, 0
	s_cbranch_scc1 .Le1_doatomic
	s_cmp_lg_u32 s26, 1
	s_cbranch_scc1 .Le1_nopeek
	s_mov_b64 s[72:73], exec
	s_mov_b64 exec, 0xff
	v_mbcnt_lo_u32_b32 v1, -1, 0
	v_lshlrev_b32_e32 v1, 8, v1
	v_add_u32_e32 v1, 0x4600, v1
	global_load_dword v1, v1, s[82:83] sc1
	s_waitcnt vmcnt(0)
	v_cmp_lt_i32_e32 vcc, v1, v153
	s_nop 1
	s_and_b32 s54, vcc_lo, 0xff
	s_mov_b64 exec, s[72:73]
.Le1_nopeek:
	s_add_i32 s55, s26, s23
	s_and_b32 s55, s55, 7
	s_lshr_b32 s55, s54, s55
	s_and_b32 s55, s55, 1
	s_cmp_lg_u32 s55, 0
	s_cbranch_scc1 .Le1_doatomic
	v_mov_b32_e32 v1, 0x7fffff00
	s_branch .LBB0_1272
.Le1_doatomic:
	s_bcnt1_i32_b64 s2, s[20:21]
	v_mov_b32_e32 v1, s2
	global_atomic_add v1, v97, v1, s[12:13] sc0
